# row-norm passes: split-K slab fold of the tail rows issues 16 loads into distinct registers behind counted waits (was one destination quad with vmcnt(0) after every load: 64/32/16 dependent round trip
# speedup vs baseline: 1.0147x; 1.0063x over previous
; __device__ __forceinline__ void norm_phase(const Params& p, const float* __restrict__ gain, int mode, int nslab) {
;     ...
;     if (nslab > 0 && r >= 32768) {
;       const float* sl = (const float*)(p.ws + OFF_SLAB) + (size_t)(r - 32768) * 1024 + lane * 4;
;       for (int sI = 0; sI < nslab; ++sI)
; #pragma unroll
;         for (int i = 0; i < 4; ++i) { const float4 a = *(const float4*)(sl + (size_t)sI * 131072 + i * 256); v[i].x += a.x; v[i].y += a.y; v[i].z += a.z; v[i].w += a.w; }
; #pragma unroll
;       for (int i = 0; i < 4; ++i) *(float4*)(hp + i * 256 + lane * 4) = v[i];
;     }
.LBB0_1032:
	v_lshl_add_u64 v[54:55], v[52:53], 0, s[6:7]
	s_add_u32 s6, s6, 0x200000
	s_addc_u32 s7, s7, 0
	v_add_co_u32_e32 v56, vcc, 0x1bb15000, v54
	s_nop 1
	v_addc_co_u32_e32 v57, vcc, 0, v55, vcc
	global_load_dwordx4 v[64:67], v[56:57], off offset:2304
	global_load_dwordx4 v[68:71], v[56:57], off offset:3328
	v_add_co_u32_e32 v58, vcc, 0x1bb16000, v54
	s_nop 1
	v_addc_co_u32_e32 v59, vcc, 0, v55, vcc
	global_load_dwordx4 v[72:75], v[58:59], off offset:256
	global_load_dwordx4 v[76:79], v[58:59], off offset:1280
	v_add_co_u32_e32 v56, vcc, 0x1bb95000, v54
	s_nop 1
	v_addc_co_u32_e32 v57, vcc, 0, v55, vcc
	global_load_dwordx4 v[80:83], v[56:57], off offset:2304
	global_load_dwordx4 v[84:87], v[56:57], off offset:3328
	v_add_co_u32_e32 v58, vcc, 0x1bb96000, v54
	s_nop 1
	v_addc_co_u32_e32 v59, vcc, 0, v55, vcc
	global_load_dwordx4 v[88:91], v[58:59], off offset:256
	global_load_dwordx4 v[92:95], v[58:59], off offset:1280
	v_add_co_u32_e32 v56, vcc, 0x1bc15000, v54
	s_nop 1
	v_addc_co_u32_e32 v57, vcc, 0, v55, vcc
	global_load_dwordx4 v[96:99], v[56:57], off offset:2304
	global_load_dwordx4 v[100:103], v[56:57], off offset:3328
	v_add_co_u32_e32 v58, vcc, 0x1bc16000, v54
	s_nop 1
	v_addc_co_u32_e32 v59, vcc, 0, v55, vcc
	global_load_dwordx4 v[104:107], v[58:59], off offset:256
	global_load_dwordx4 v[108:111], v[58:59], off offset:1280
	v_add_co_u32_e32 v56, vcc, 0x1bc95000, v54
	s_nop 1
	v_addc_co_u32_e32 v57, vcc, 0, v55, vcc
	global_load_dwordx4 v[112:115], v[56:57], off offset:2304
	global_load_dwordx4 v[116:119], v[56:57], off offset:3328
	v_add_co_u32_e32 v58, vcc, 0x1bc96000, v54
	s_nop 1
	v_addc_co_u32_e32 v59, vcc, 0, v55, vcc
	global_load_dwordx4 v[120:123], v[58:59], off offset:256
	global_load_dwordx4 v[124:127], v[58:59], off offset:1280
	s_waitcnt vmcnt(15)
	v_pk_add_f32 v[32:33], v[32:33], v[64:65]
	v_pk_add_f32 v[34:35], v[34:35], v[66:67]
	s_waitcnt vmcnt(14)
	v_pk_add_f32 v[28:29], v[28:29], v[68:69]
	v_pk_add_f32 v[30:31], v[30:31], v[70:71]
	s_waitcnt vmcnt(13)
	v_pk_add_f32 v[24:25], v[24:25], v[72:73]
	v_pk_add_f32 v[26:27], v[26:27], v[74:75]
	s_waitcnt vmcnt(12)
	v_pk_add_f32 v[20:21], v[20:21], v[76:77]
	v_pk_add_f32 v[22:23], v[22:23], v[78:79]
	s_waitcnt vmcnt(11)
	v_pk_add_f32 v[32:33], v[32:33], v[80:81]
	v_pk_add_f32 v[34:35], v[34:35], v[82:83]
	s_waitcnt vmcnt(10)
	v_pk_add_f32 v[28:29], v[28:29], v[84:85]
	v_pk_add_f32 v[30:31], v[30:31], v[86:87]
	s_waitcnt vmcnt(9)
	v_pk_add_f32 v[24:25], v[24:25], v[88:89]
	v_pk_add_f32 v[26:27], v[26:27], v[90:91]
	s_waitcnt vmcnt(8)
	v_pk_add_f32 v[20:21], v[20:21], v[92:93]
	v_pk_add_f32 v[22:23], v[22:23], v[94:95]
	s_waitcnt vmcnt(7)
	v_pk_add_f32 v[32:33], v[32:33], v[96:97]
	v_pk_add_f32 v[34:35], v[34:35], v[98:99]
	s_waitcnt vmcnt(6)
	v_pk_add_f32 v[28:29], v[28:29], v[100:101]
	v_pk_add_f32 v[30:31], v[30:31], v[102:103]
	s_waitcnt vmcnt(5)
	v_pk_add_f32 v[24:25], v[24:25], v[104:105]
	v_pk_add_f32 v[26:27], v[26:27], v[106:107]
	s_waitcnt vmcnt(4)
	v_pk_add_f32 v[20:21], v[20:21], v[108:109]
	v_pk_add_f32 v[22:23], v[22:23], v[110:111]
	s_waitcnt vmcnt(3)
	v_pk_add_f32 v[32:33], v[32:33], v[112:113]
	v_pk_add_f32 v[34:35], v[34:35], v[114:115]
	s_waitcnt vmcnt(2)
	v_pk_add_f32 v[28:29], v[28:29], v[116:117]
	v_pk_add_f32 v[30:31], v[30:31], v[118:119]
	s_waitcnt vmcnt(1)
	v_pk_add_f32 v[24:25], v[24:25], v[120:121]
	v_pk_add_f32 v[26:27], v[26:27], v[122:123]
	s_waitcnt vmcnt(0)
	v_pk_add_f32 v[20:21], v[20:21], v[124:125]
	v_pk_add_f32 v[22:23], v[22:23], v[126:127]
	s_cmp_eq_u32 s6, 0x800000
	s_cbranch_scc0 .LBB0_1032
	v_lshlrev_b64 v[48:49], 12, v[48:49]
	v_lshl_add_u64 v[48:49], v[50:51], 0, v[48:49]
	v_mov_b32_e32 v45, v130
	v_lshl_add_u64 v[48:49], v[48:49], 0, v[44:45]
	global_store_dwordx4 v[48:49], v[32:35], off
	global_store_dwordx4 v[48:49], v[28:31], off offset:1024
	global_store_dwordx4 v[48:49], v[24:27], off offset:2048
	global_store_dwordx4 v[48:49], v[20:23], off offset:3072
	s_branch .LBB0_1019

; __device__ __forceinline__ void norm_phase(const Params& p, const float* __restrict__ gain, int mode, int nslab) {
;     ...
;     if (nslab > 0 && r >= 32768) {
;       const float* sl = (const float*)(p.ws + OFF_SLAB) + (size_t)(r - 32768) * 1024 + lane * 4;
;       for (int sI = 0; sI < nslab; ++sI)
; #pragma unroll
;         for (int i = 0; i < 4; ++i) { const float4 a = *(const float4*)(sl + (size_t)sI * 131072 + i * 256); v[i].x += a.x; v[i].y += a.y; v[i].z += a.z; v[i].w += a.w; }
; #pragma unroll
;       for (int i = 0; i < 4; ++i) *(float4*)(hp + i * 256 + lane * 4) = v[i];
;     }
.LBB0_2110:
	s_or_b64 exec, exec, s[8:9]
	s_and_b64 s[0:1], exec, vcc
	s_or_b64 s[4:5], s[0:1], s[4:5]
	v_cmp_lt_i32_e32 vcc, s19, v46
	s_and_saveexec_b64 s[0:1], vcc
	s_cbranch_execz .LBB0_2091
	v_mov_b32_e32 v45, v130
	v_lshlrev_b64 v[52:53], 12, v[44:45]
	v_lshl_add_u64 v[52:53], v[42:43], 0, v[52:53]
	s_mov_b32 s8, s18
	s_and_b32 s10, s18, 3
	s_cmp_lg_u32 s10, 0
	s_cbranch_scc1 .LBB0_2112
	s_cmp_lt_u32 s18, 4
	s_cbranch_scc1 .LBB0_2112
	s_mov_b64 s[10:11], 0x80000
.Lmn_loop4:
	global_load_dwordx4 v[64:67], v[52:53], off
	global_load_dwordx4 v[68:71], v[52:53], off offset:1024
	global_load_dwordx4 v[72:75], v[52:53], off offset:2048
	global_load_dwordx4 v[76:79], v[52:53], off offset:3072
	v_lshl_add_u64 v[52:53], v[52:53], 0, s[10:11]
	global_load_dwordx4 v[80:83], v[52:53], off
	global_load_dwordx4 v[84:87], v[52:53], off offset:1024
	global_load_dwordx4 v[88:91], v[52:53], off offset:2048
	global_load_dwordx4 v[92:95], v[52:53], off offset:3072
	v_lshl_add_u64 v[52:53], v[52:53], 0, s[10:11]
	global_load_dwordx4 v[96:99], v[52:53], off
	global_load_dwordx4 v[100:103], v[52:53], off offset:1024
	global_load_dwordx4 v[104:107], v[52:53], off offset:2048
	global_load_dwordx4 v[108:111], v[52:53], off offset:3072
	v_lshl_add_u64 v[52:53], v[52:53], 0, s[10:11]
	global_load_dwordx4 v[112:115], v[52:53], off
	global_load_dwordx4 v[116:119], v[52:53], off offset:1024
	global_load_dwordx4 v[120:123], v[52:53], off offset:2048
	global_load_dwordx4 v[124:127], v[52:53], off offset:3072
	v_lshl_add_u64 v[52:53], v[52:53], 0, s[10:11]
	s_waitcnt vmcnt(15)
	v_pk_add_f32 v[32:33], v[32:33], v[64:65]
	v_pk_add_f32 v[34:35], v[34:35], v[66:67]
	s_waitcnt vmcnt(14)
	v_pk_add_f32 v[28:29], v[28:29], v[68:69]
	v_pk_add_f32 v[30:31], v[30:31], v[70:71]
	s_waitcnt vmcnt(13)
	v_pk_add_f32 v[8:9], v[8:9], v[72:73]
	v_pk_add_f32 v[10:11], v[10:11], v[74:75]
	s_waitcnt vmcnt(12)
	v_pk_add_f32 v[0:1], v[0:1], v[76:77]
	v_pk_add_f32 v[2:3], v[2:3], v[78:79]
	s_waitcnt vmcnt(11)
	v_pk_add_f32 v[32:33], v[32:33], v[80:81]
	v_pk_add_f32 v[34:35], v[34:35], v[82:83]
	s_waitcnt vmcnt(10)
	v_pk_add_f32 v[28:29], v[28:29], v[84:85]
	v_pk_add_f32 v[30:31], v[30:31], v[86:87]
	s_waitcnt vmcnt(9)
	v_pk_add_f32 v[8:9], v[8:9], v[88:89]
	v_pk_add_f32 v[10:11], v[10:11], v[90:91]
	s_waitcnt vmcnt(8)
	v_pk_add_f32 v[0:1], v[0:1], v[92:93]
	v_pk_add_f32 v[2:3], v[2:3], v[94:95]
	s_waitcnt vmcnt(7)
	v_pk_add_f32 v[32:33], v[32:33], v[96:97]
	v_pk_add_f32 v[34:35], v[34:35], v[98:99]
	s_waitcnt vmcnt(6)
	v_pk_add_f32 v[28:29], v[28:29], v[100:101]
	v_pk_add_f32 v[30:31], v[30:31], v[102:103]
	s_waitcnt vmcnt(5)
	v_pk_add_f32 v[8:9], v[8:9], v[104:105]
	v_pk_add_f32 v[10:11], v[10:11], v[106:107]
	s_waitcnt vmcnt(4)
	v_pk_add_f32 v[0:1], v[0:1], v[108:109]
	v_pk_add_f32 v[2:3], v[2:3], v[110:111]
	s_waitcnt vmcnt(3)
	v_pk_add_f32 v[32:33], v[32:33], v[112:113]
	v_pk_add_f32 v[34:35], v[34:35], v[114:115]
	s_waitcnt vmcnt(2)
	v_pk_add_f32 v[28:29], v[28:29], v[116:117]
	v_pk_add_f32 v[30:31], v[30:31], v[118:119]
	s_waitcnt vmcnt(1)
	v_pk_add_f32 v[8:9], v[8:9], v[120:121]
	v_pk_add_f32 v[10:11], v[10:11], v[122:123]
	s_waitcnt vmcnt(0)
	v_pk_add_f32 v[0:1], v[0:1], v[124:125]
	v_pk_add_f32 v[2:3], v[2:3], v[126:127]
	s_add_i32 s8, s8, -4
	s_cmp_eq_u32 s8, 0
	s_cbranch_scc0 .Lmn_loop4
	s_branch .Lmn_done

; __device__ __forceinline__ void norm_phase(const Params& p, const float* __restrict__ gain, int mode, int nslab) {
;     ...
;       for (int i = 0; i < 4; ++i) *(float4*)(hp + i * 256 + lane * 4) = v[i];
.Lmn_done:
	v_lshlrev_b64 v[48:49], 12, v[48:49]
	v_lshl_add_u64 v[48:49], v[50:51], 0, v[48:49]
	v_lshlrev_b32_e32 v50, 2, v36
	v_mov_b32_e32 v51, v130
	v_lshl_add_u64 v[48:49], v[48:49], 0, v[50:51]
	global_store_dwordx4 v[48:49], v[32:35], off
	global_store_dwordx4 v[48:49], v[28:31], off offset:1024
	global_store_dwordx4 v[48:49], v[8:11], off offset:2048
	global_store_dwordx4 v[48:49], v[0:3], off offset:3072
	s_branch .LBB0_2091
